# adaLN GEMV k-loop software-pipelined in place: next k-step weight loads issued as each register group is consumed
# speedup vs baseline: 1.0110x; 1.0110x over previous
.LBB0_21:
	v_add_u32_e32 v3, 0x200, v3
	v_and_b32_e32 v4, 0x3fff, v3
	v_add_u32_e32 v54, 0xfffff800, v4
	v_lshl_add_u64 v[4:5], v[54:55], 2, s[16:17]
	global_load_dword v4, v[4:5], off
	v_cmp_lt_u32_e32 vcc, s18, v3
	s_or_b64 s[14:15], vcc, s[14:15]
	s_waitcnt vmcnt(0)
	v_mul_f32_e32 v5, 0xbfb8aa3b, v4
	v_exp_f32_e32 v5, v5
	s_nop 0
	v_add_f32_e32 v5, 1.0, v5
	v_div_scale_f32 v6, s[8:9], v5, v5, v4
	v_rcp_f32_e32 v7, v6
	v_div_scale_f32 v8, vcc, v4, v5, v4
	v_fma_f32 v9, -v6, v7, 1.0
	v_fmac_f32_e32 v7, v9, v7
	v_mul_f32_e32 v9, v8, v7
	v_fma_f32 v10, -v6, v9, v8
	v_fmac_f32_e32 v9, v10, v7
	v_fma_f32 v6, -v6, v9, v8
	v_div_fmas_f32 v6, v6, v7, v9
	v_div_fixup_f32 v4, v6, v5, v4
	ds_write_b32 v2, v4
	v_add_u32_e32 v2, 0x800, v2
	s_andn2_b64 exec, exec, s[14:15]
	s_cbranch_execnz .LBB0_21
	s_or_b64 exec, exec, s[14:15]
	s_ashr_i32 s12, s28, 7
	s_waitcnt lgkmcnt(0)
	s_barrier
	s_and_saveexec_b64 s[8:9], s[6:7]
	s_cbranch_execz .LBB0_26
	s_and_b32 s13, s27, 0x7f
	v_readlane_b32 s10, v253, 3
	v_readlane_b32 s11, v253, 4
	s_add_u32 s10, s10, s0
	s_addc_u32 s11, s11, s1
	s_load_dwordx2 s[10:11], s[10:11], 0x60
	s_mul_i32 s14, s12, 0x6000000
	s_mulk_i32 s13, 0x180
	s_mul_hi_i32 s15, s12, 0x6000000
	s_or_b32 s14, s14, s13
	s_waitcnt lgkmcnt(0)
	v_lshl_add_u64 v[2:3], s[10:11], 0, v[64:65]
	v_mov_b32_e32 v6, 0
	v_lshl_add_u64 v[66:67], v[2:3], 0, s[14:15]
	s_mov_b64 s[10:11], 0
	v_mov_b32_e32 v54, v1
	v_mov_b32_e32 v7, v6
	v_mov_b32_e32 v8, v6
	v_mov_b32_e32 v9, v6
	v_mov_b32_e32 v18, v6
	v_mov_b32_e32 v19, v6
	v_mov_b32_e32 v20, v6
	v_mov_b32_e32 v21, v6
	v_mov_b32_e32 v14, v6
	v_mov_b32_e32 v15, v6
	v_mov_b32_e32 v16, v6
	v_mov_b32_e32 v17, v6
	v_mov_b32_e32 v10, v6
	v_mov_b32_e32 v11, v6
	v_mov_b32_e32 v12, v6
	v_mov_b32_e32 v13, v6
	v_mov_b32_e32 v2, v6
	v_mov_b32_e32 v3, v6
	v_mov_b32_e32 v4, v6
	v_mov_b32_e32 v5, v6
	v_lshl_add_u64 v[150:151], v[66:67], 0, s[10:11]
	v_add_co_u32_e32 v152, vcc, s19, v150
	s_nop 1
	v_addc_co_u32_e32 v153, vcc, 0, v151, vcc
	v_add_co_u32_e32 v154, vcc, s19, v152
	s_nop 1
	v_addc_co_u32_e32 v155, vcc, 0, v153, vcc
	v_add_co_u32_e32 v156, vcc, s19, v154
	s_nop 1
	v_addc_co_u32_e32 v157, vcc, 0, v155, vcc
	v_add_co_u32_e32 v158, vcc, s19, v156
	s_nop 1
	v_addc_co_u32_e32 v159, vcc, 0, v157, vcc
	v_add_co_u32_e32 v160, vcc, s19, v158
	s_nop 1
	v_addc_co_u32_e32 v161, vcc, 0, v159, vcc
	v_add_co_u32_e32 v162, vcc, s19, v160
	s_nop 1
	v_addc_co_u32_e32 v163, vcc, 0, v161, vcc
	v_add_co_u32_e32 v164, vcc, s19, v162
	s_nop 1
	v_addc_co_u32_e32 v165, vcc, 0, v163, vcc
	global_load_dwordx4 v[84:87], v[150:151], off nt
	global_load_dwordx4 v[88:91], v[152:153], off nt
	global_load_dwordx4 v[92:95], v[154:155], off nt
	global_load_dwordx4 v[96:99], v[156:157], off nt
	global_load_dwordx4 v[100:103], v[158:159], off nt
	global_load_dwordx4 v[104:107], v[160:161], off nt
	global_load_dwordx4 v[108:111], v[162:163], off nt
	global_load_dwordx4 v[112:115], v[164:165], off nt
.Lgv_loop:
	ds_read_b128 v[26:29], v54
	ds_read_b128 v[22:25], v54 offset:16
	ds_read_b128 v[30:33], v54 offset:8192
	ds_read_b128 v[34:37], v54 offset:8208
	ds_read_b128 v[50:53], v54 offset:16384
	ds_read_b128 v[38:41], v54 offset:16400
	ds_read_b128 v[76:79], v54 offset:24576
	ds_read_b128 v[42:45], v54 offset:24592
	ds_read_b128 v[80:83], v54 offset:32768
	ds_read_b128 v[46:49], v54 offset:32784
	s_waitcnt lgkmcnt(8)
	v_mov_b32_e32 v124, v25
	s_waitcnt lgkmcnt(6)
	v_mov_b32_e32 v126, v37
	s_waitcnt lgkmcnt(4)
	v_mov_b32_e32 v128, v41
	v_mov_b32_e32 v68, v29
	v_mov_b32_e32 v116, v33
	v_mov_b32_e32 v118, v53
	s_waitcnt lgkmcnt(3)
	v_mov_b32_e32 v120, v79
	s_waitcnt lgkmcnt(1)
	v_mov_b32_e32 v122, v83
	v_mov_b32_e32 v130, v45
	s_waitcnt lgkmcnt(0)
	v_mov_b32_e32 v132, v49
	v_add_u32_e32 v54, 32, v54
	s_add_u32 s10, s10, 0x60000
	s_addc_u32 s11, s11, 0
	s_cmp_lg_u32 s10, 0x600000
	s_cbranch_scc0 .Lgv_last
	v_lshl_add_u64 v[150:151], v[66:67], 0, s[10:11]
	v_add_co_u32_e32 v152, vcc, s19, v150
	s_nop 1
	v_addc_co_u32_e32 v153, vcc, 0, v151, vcc
	v_add_co_u32_e32 v154, vcc, s19, v152
	s_nop 1
	v_addc_co_u32_e32 v155, vcc, 0, v153, vcc
	v_add_co_u32_e32 v156, vcc, s19, v154
	s_nop 1
	v_addc_co_u32_e32 v157, vcc, 0, v155, vcc
	v_add_co_u32_e32 v158, vcc, s19, v156
	s_nop 1
	v_addc_co_u32_e32 v159, vcc, 0, v157, vcc
	v_add_co_u32_e32 v160, vcc, s19, v158
	s_nop 1
	v_addc_co_u32_e32 v161, vcc, 0, v159, vcc
	v_add_co_u32_e32 v162, vcc, s19, v160
	s_nop 1
	v_addc_co_u32_e32 v163, vcc, 0, v161, vcc
	v_add_co_u32_e32 v164, vcc, s19, v162
	s_nop 1
	v_addc_co_u32_e32 v165, vcc, 0, v163, vcc
	s_waitcnt vmcnt(7)
	v_pk_fma_f32 v[6:7], v[84:85], v[26:27], v[6:7] op_sel_hi:[1,0,1]
	v_pk_fma_f32 v[8:9], v[86:87], v[26:27], v[8:9] op_sel_hi:[1,0,1]
	v_pk_fma_f32 v[18:19], v[84:85], v[30:31], v[18:19] op_sel_hi:[1,0,1]
	v_pk_fma_f32 v[20:21], v[86:87], v[30:31], v[20:21] op_sel_hi:[1,0,1]
	v_pk_fma_f32 v[14:15], v[84:85], v[50:51], v[14:15] op_sel_hi:[1,0,1]
	v_pk_fma_f32 v[16:17], v[86:87], v[50:51], v[16:17] op_sel_hi:[1,0,1]
	v_pk_fma_f32 v[10:11], v[84:85], v[76:77], v[10:11] op_sel_hi:[1,0,1]
	v_pk_fma_f32 v[12:13], v[86:87], v[76:77], v[12:13] op_sel_hi:[1,0,1]
	v_pk_fma_f32 v[2:3], v[84:85], v[80:81], v[2:3] op_sel_hi:[1,0,1]
	v_pk_fma_f32 v[4:5], v[86:87], v[80:81], v[4:5] op_sel_hi:[1,0,1]
	global_load_dwordx4 v[84:87], v[150:151], off nt
	s_waitcnt vmcnt(7)
	v_pk_fma_f32 v[6:7], v[88:89], v[26:27], v[6:7] op_sel:[0,1,0]
	v_pk_fma_f32 v[8:9], v[90:91], v[26:27], v[8:9] op_sel:[0,1,0]
	v_pk_fma_f32 v[18:19], v[88:89], v[30:31], v[18:19] op_sel:[0,1,0]
	v_pk_fma_f32 v[20:21], v[90:91], v[30:31], v[20:21] op_sel:[0,1,0]
	v_pk_fma_f32 v[14:15], v[88:89], v[50:51], v[14:15] op_sel:[0,1,0]
	v_pk_fma_f32 v[16:17], v[90:91], v[50:51], v[16:17] op_sel:[0,1,0]
	v_pk_fma_f32 v[10:11], v[88:89], v[76:77], v[10:11] op_sel:[0,1,0]
	v_pk_fma_f32 v[12:13], v[90:91], v[76:77], v[12:13] op_sel:[0,1,0]
	v_pk_fma_f32 v[2:3], v[88:89], v[80:81], v[2:3] op_sel:[0,1,0]
	v_pk_fma_f32 v[4:5], v[90:91], v[80:81], v[4:5] op_sel:[0,1,0]
	global_load_dwordx4 v[88:91], v[152:153], off nt
	s_waitcnt vmcnt(7)
	v_pk_fma_f32 v[6:7], v[92:93], v[28:29], v[6:7] op_sel_hi:[1,0,1]
	v_pk_fma_f32 v[8:9], v[94:95], v[28:29], v[8:9] op_sel_hi:[1,0,1]
	v_pk_fma_f32 v[18:19], v[92:93], v[32:33], v[18:19] op_sel_hi:[1,0,1]
	v_pk_fma_f32 v[20:21], v[94:95], v[32:33], v[20:21] op_sel_hi:[1,0,1]
	v_pk_fma_f32 v[14:15], v[92:93], v[52:53], v[14:15] op_sel_hi:[1,0,1]
	v_pk_fma_f32 v[16:17], v[94:95], v[52:53], v[16:17] op_sel_hi:[1,0,1]
	v_pk_fma_f32 v[10:11], v[92:93], v[78:79], v[10:11] op_sel_hi:[1,0,1]
	v_pk_fma_f32 v[12:13], v[94:95], v[78:79], v[12:13] op_sel_hi:[1,0,1]
	v_pk_fma_f32 v[2:3], v[92:93], v[82:83], v[2:3] op_sel_hi:[1,0,1]
	v_pk_fma_f32 v[4:5], v[94:95], v[82:83], v[4:5] op_sel_hi:[1,0,1]
	global_load_dwordx4 v[92:95], v[154:155], off nt
	s_waitcnt vmcnt(7)
	v_pk_fma_f32 v[6:7], v[96:97], v[68:69], v[6:7] op_sel_hi:[1,0,1]
	v_pk_fma_f32 v[8:9], v[98:99], v[68:69], v[8:9] op_sel_hi:[1,0,1]
	v_pk_fma_f32 v[18:19], v[96:97], v[116:117], v[18:19] op_sel_hi:[1,0,1]
	v_pk_fma_f32 v[20:21], v[98:99], v[116:117], v[20:21] op_sel_hi:[1,0,1]
	v_pk_fma_f32 v[14:15], v[96:97], v[118:119], v[14:15] op_sel_hi:[1,0,1]
	v_pk_fma_f32 v[16:17], v[98:99], v[118:119], v[16:17] op_sel_hi:[1,0,1]
	v_pk_fma_f32 v[10:11], v[96:97], v[120:121], v[10:11] op_sel_hi:[1,0,1]
	v_pk_fma_f32 v[12:13], v[98:99], v[120:121], v[12:13] op_sel_hi:[1,0,1]
	v_pk_fma_f32 v[2:3], v[96:97], v[122:123], v[2:3] op_sel_hi:[1,0,1]
	v_pk_fma_f32 v[4:5], v[98:99], v[122:123], v[4:5] op_sel_hi:[1,0,1]
	global_load_dwordx4 v[96:99], v[156:157], off nt
	s_waitcnt vmcnt(7)
	v_pk_fma_f32 v[6:7], v[100:101], v[22:23], v[6:7] op_sel_hi:[1,0,1]
	v_pk_fma_f32 v[8:9], v[102:103], v[22:23], v[8:9] op_sel_hi:[1,0,1]
	v_pk_fma_f32 v[18:19], v[100:101], v[34:35], v[18:19] op_sel_hi:[1,0,1]
	v_pk_fma_f32 v[20:21], v[102:103], v[34:35], v[20:21] op_sel_hi:[1,0,1]
	v_pk_fma_f32 v[14:15], v[100:101], v[38:39], v[14:15] op_sel_hi:[1,0,1]
	v_pk_fma_f32 v[16:17], v[102:103], v[38:39], v[16:17] op_sel_hi:[1,0,1]
	v_pk_fma_f32 v[10:11], v[100:101], v[42:43], v[10:11] op_sel_hi:[1,0,1]
	v_pk_fma_f32 v[12:13], v[102:103], v[42:43], v[12:13] op_sel_hi:[1,0,1]
	v_pk_fma_f32 v[2:3], v[100:101], v[46:47], v[2:3] op_sel_hi:[1,0,1]
	v_pk_fma_f32 v[4:5], v[102:103], v[46:47], v[4:5] op_sel_hi:[1,0,1]
	global_load_dwordx4 v[100:103], v[158:159], off nt
	s_waitcnt vmcnt(7)
	v_pk_fma_f32 v[6:7], v[104:105], v[22:23], v[6:7] op_sel:[0,1,0]
	v_pk_fma_f32 v[8:9], v[106:107], v[22:23], v[8:9] op_sel:[0,1,0]
	v_pk_fma_f32 v[18:19], v[104:105], v[34:35], v[18:19] op_sel:[0,1,0]
	v_pk_fma_f32 v[20:21], v[106:107], v[34:35], v[20:21] op_sel:[0,1,0]
	v_pk_fma_f32 v[14:15], v[104:105], v[38:39], v[14:15] op_sel:[0,1,0]
	v_pk_fma_f32 v[16:17], v[106:107], v[38:39], v[16:17] op_sel:[0,1,0]
	v_pk_fma_f32 v[10:11], v[104:105], v[42:43], v[10:11] op_sel:[0,1,0]
	v_pk_fma_f32 v[12:13], v[106:107], v[42:43], v[12:13] op_sel:[0,1,0]
	v_pk_fma_f32 v[2:3], v[104:105], v[46:47], v[2:3] op_sel:[0,1,0]
	v_pk_fma_f32 v[4:5], v[106:107], v[46:47], v[4:5] op_sel:[0,1,0]
	global_load_dwordx4 v[104:107], v[160:161], off nt
	s_waitcnt vmcnt(7)
	v_pk_fma_f32 v[6:7], v[108:109], v[24:25], v[6:7] op_sel_hi:[1,0,1]
	v_pk_fma_f32 v[8:9], v[110:111], v[24:25], v[8:9] op_sel_hi:[1,0,1]
	v_pk_fma_f32 v[18:19], v[108:109], v[36:37], v[18:19] op_sel_hi:[1,0,1]
	v_pk_fma_f32 v[20:21], v[110:111], v[36:37], v[20:21] op_sel_hi:[1,0,1]
	v_pk_fma_f32 v[14:15], v[108:109], v[40:41], v[14:15] op_sel_hi:[1,0,1]
	v_pk_fma_f32 v[16:17], v[110:111], v[40:41], v[16:17] op_sel_hi:[1,0,1]
	v_pk_fma_f32 v[10:11], v[108:109], v[44:45], v[10:11] op_sel_hi:[1,0,1]
	v_pk_fma_f32 v[12:13], v[110:111], v[44:45], v[12:13] op_sel_hi:[1,0,1]
	v_pk_fma_f32 v[2:3], v[108:109], v[48:49], v[2:3] op_sel_hi:[1,0,1]
	v_pk_fma_f32 v[4:5], v[110:111], v[48:49], v[4:5] op_sel_hi:[1,0,1]
	global_load_dwordx4 v[108:111], v[162:163], off nt
	s_waitcnt vmcnt(7)
	v_pk_fma_f32 v[6:7], v[112:113], v[124:125], v[6:7] op_sel_hi:[1,0,1]
	v_pk_fma_f32 v[8:9], v[114:115], v[124:125], v[8:9] op_sel_hi:[1,0,1]
	v_pk_fma_f32 v[18:19], v[112:113], v[126:127], v[18:19] op_sel_hi:[1,0,1]
	v_pk_fma_f32 v[20:21], v[114:115], v[126:127], v[20:21] op_sel_hi:[1,0,1]
	v_pk_fma_f32 v[14:15], v[112:113], v[128:129], v[14:15] op_sel_hi:[1,0,1]
	v_pk_fma_f32 v[16:17], v[114:115], v[128:129], v[16:17] op_sel_hi:[1,0,1]
	v_pk_fma_f32 v[10:11], v[112:113], v[130:131], v[10:11] op_sel_hi:[1,0,1]
	v_pk_fma_f32 v[12:13], v[114:115], v[130:131], v[12:13] op_sel_hi:[1,0,1]
	v_pk_fma_f32 v[2:3], v[112:113], v[132:133], v[2:3] op_sel_hi:[1,0,1]
	v_pk_fma_f32 v[4:5], v[114:115], v[132:133], v[4:5] op_sel_hi:[1,0,1]
	global_load_dwordx4 v[112:115], v[164:165], off nt
	s_branch .Lgv_loop
.Lgv_last:
	s_waitcnt vmcnt(7)
	v_pk_fma_f32 v[6:7], v[84:85], v[26:27], v[6:7] op_sel_hi:[1,0,1]
	v_pk_fma_f32 v[8:9], v[86:87], v[26:27], v[8:9] op_sel_hi:[1,0,1]
	v_pk_fma_f32 v[18:19], v[84:85], v[30:31], v[18:19] op_sel_hi:[1,0,1]
	v_pk_fma_f32 v[20:21], v[86:87], v[30:31], v[20:21] op_sel_hi:[1,0,1]
	v_pk_fma_f32 v[14:15], v[84:85], v[50:51], v[14:15] op_sel_hi:[1,0,1]
	v_pk_fma_f32 v[16:17], v[86:87], v[50:51], v[16:17] op_sel_hi:[1,0,1]
	v_pk_fma_f32 v[10:11], v[84:85], v[76:77], v[10:11] op_sel_hi:[1,0,1]
	v_pk_fma_f32 v[12:13], v[86:87], v[76:77], v[12:13] op_sel_hi:[1,0,1]
	v_pk_fma_f32 v[2:3], v[84:85], v[80:81], v[2:3] op_sel_hi:[1,0,1]
	v_pk_fma_f32 v[4:5], v[86:87], v[80:81], v[4:5] op_sel_hi:[1,0,1]
	s_waitcnt vmcnt(6)
	v_pk_fma_f32 v[6:7], v[88:89], v[26:27], v[6:7] op_sel:[0,1,0]
	v_pk_fma_f32 v[8:9], v[90:91], v[26:27], v[8:9] op_sel:[0,1,0]
	v_pk_fma_f32 v[18:19], v[88:89], v[30:31], v[18:19] op_sel:[0,1,0]
	v_pk_fma_f32 v[20:21], v[90:91], v[30:31], v[20:21] op_sel:[0,1,0]
	v_pk_fma_f32 v[14:15], v[88:89], v[50:51], v[14:15] op_sel:[0,1,0]
	v_pk_fma_f32 v[16:17], v[90:91], v[50:51], v[16:17] op_sel:[0,1,0]
	v_pk_fma_f32 v[10:11], v[88:89], v[76:77], v[10:11] op_sel:[0,1,0]
	v_pk_fma_f32 v[12:13], v[90:91], v[76:77], v[12:13] op_sel:[0,1,0]
	v_pk_fma_f32 v[2:3], v[88:89], v[80:81], v[2:3] op_sel:[0,1,0]
	v_pk_fma_f32 v[4:5], v[90:91], v[80:81], v[4:5] op_sel:[0,1,0]
	s_waitcnt vmcnt(5)
	v_pk_fma_f32 v[6:7], v[92:93], v[28:29], v[6:7] op_sel_hi:[1,0,1]
	v_pk_fma_f32 v[8:9], v[94:95], v[28:29], v[8:9] op_sel_hi:[1,0,1]
	v_pk_fma_f32 v[18:19], v[92:93], v[32:33], v[18:19] op_sel_hi:[1,0,1]
	v_pk_fma_f32 v[20:21], v[94:95], v[32:33], v[20:21] op_sel_hi:[1,0,1]
	v_pk_fma_f32 v[14:15], v[92:93], v[52:53], v[14:15] op_sel_hi:[1,0,1]
	v_pk_fma_f32 v[16:17], v[94:95], v[52:53], v[16:17] op_sel_hi:[1,0,1]
	v_pk_fma_f32 v[10:11], v[92:93], v[78:79], v[10:11] op_sel_hi:[1,0,1]
	v_pk_fma_f32 v[12:13], v[94:95], v[78:79], v[12:13] op_sel_hi:[1,0,1]
	v_pk_fma_f32 v[2:3], v[92:93], v[82:83], v[2:3] op_sel_hi:[1,0,1]
	v_pk_fma_f32 v[4:5], v[94:95], v[82:83], v[4:5] op_sel_hi:[1,0,1]
	s_waitcnt vmcnt(4)
	v_pk_fma_f32 v[6:7], v[96:97], v[68:69], v[6:7] op_sel_hi:[1,0,1]
	v_pk_fma_f32 v[8:9], v[98:99], v[68:69], v[8:9] op_sel_hi:[1,0,1]
	v_pk_fma_f32 v[18:19], v[96:97], v[116:117], v[18:19] op_sel_hi:[1,0,1]
	v_pk_fma_f32 v[20:21], v[98:99], v[116:117], v[20:21] op_sel_hi:[1,0,1]
	v_pk_fma_f32 v[14:15], v[96:97], v[118:119], v[14:15] op_sel_hi:[1,0,1]
	v_pk_fma_f32 v[16:17], v[98:99], v[118:119], v[16:17] op_sel_hi:[1,0,1]
	v_pk_fma_f32 v[10:11], v[96:97], v[120:121], v[10:11] op_sel_hi:[1,0,1]
	v_pk_fma_f32 v[12:13], v[98:99], v[120:121], v[12:13] op_sel_hi:[1,0,1]
	v_pk_fma_f32 v[2:3], v[96:97], v[122:123], v[2:3] op_sel_hi:[1,0,1]
	v_pk_fma_f32 v[4:5], v[98:99], v[122:123], v[4:5] op_sel_hi:[1,0,1]
	s_waitcnt vmcnt(3)
	v_pk_fma_f32 v[6:7], v[100:101], v[22:23], v[6:7] op_sel_hi:[1,0,1]
	v_pk_fma_f32 v[8:9], v[102:103], v[22:23], v[8:9] op_sel_hi:[1,0,1]
	v_pk_fma_f32 v[18:19], v[100:101], v[34:35], v[18:19] op_sel_hi:[1,0,1]
	v_pk_fma_f32 v[20:21], v[102:103], v[34:35], v[20:21] op_sel_hi:[1,0,1]
	v_pk_fma_f32 v[14:15], v[100:101], v[38:39], v[14:15] op_sel_hi:[1,0,1]
	v_pk_fma_f32 v[16:17], v[102:103], v[38:39], v[16:17] op_sel_hi:[1,0,1]
	v_pk_fma_f32 v[10:11], v[100:101], v[42:43], v[10:11] op_sel_hi:[1,0,1]
	v_pk_fma_f32 v[12:13], v[102:103], v[42:43], v[12:13] op_sel_hi:[1,0,1]
	v_pk_fma_f32 v[2:3], v[100:101], v[46:47], v[2:3] op_sel_hi:[1,0,1]
	v_pk_fma_f32 v[4:5], v[102:103], v[46:47], v[4:5] op_sel_hi:[1,0,1]
	s_waitcnt vmcnt(2)
	v_pk_fma_f32 v[6:7], v[104:105], v[22:23], v[6:7] op_sel:[0,1,0]
	v_pk_fma_f32 v[8:9], v[106:107], v[22:23], v[8:9] op_sel:[0,1,0]
	v_pk_fma_f32 v[18:19], v[104:105], v[34:35], v[18:19] op_sel:[0,1,0]
	v_pk_fma_f32 v[20:21], v[106:107], v[34:35], v[20:21] op_sel:[0,1,0]
	v_pk_fma_f32 v[14:15], v[104:105], v[38:39], v[14:15] op_sel:[0,1,0]
	v_pk_fma_f32 v[16:17], v[106:107], v[38:39], v[16:17] op_sel:[0,1,0]
	v_pk_fma_f32 v[10:11], v[104:105], v[42:43], v[10:11] op_sel:[0,1,0]
	v_pk_fma_f32 v[12:13], v[106:107], v[42:43], v[12:13] op_sel:[0,1,0]
	v_pk_fma_f32 v[2:3], v[104:105], v[46:47], v[2:3] op_sel:[0,1,0]
	v_pk_fma_f32 v[4:5], v[106:107], v[46:47], v[4:5] op_sel:[0,1,0]
	s_waitcnt vmcnt(1)
	v_pk_fma_f32 v[6:7], v[108:109], v[24:25], v[6:7] op_sel_hi:[1,0,1]
	v_pk_fma_f32 v[8:9], v[110:111], v[24:25], v[8:9] op_sel_hi:[1,0,1]
	v_pk_fma_f32 v[18:19], v[108:109], v[36:37], v[18:19] op_sel_hi:[1,0,1]
	v_pk_fma_f32 v[20:21], v[110:111], v[36:37], v[20:21] op_sel_hi:[1,0,1]
	v_pk_fma_f32 v[14:15], v[108:109], v[40:41], v[14:15] op_sel_hi:[1,0,1]
	v_pk_fma_f32 v[16:17], v[110:111], v[40:41], v[16:17] op_sel_hi:[1,0,1]
	v_pk_fma_f32 v[10:11], v[108:109], v[44:45], v[10:11] op_sel_hi:[1,0,1]
	v_pk_fma_f32 v[12:13], v[110:111], v[44:45], v[12:13] op_sel_hi:[1,0,1]
	v_pk_fma_f32 v[2:3], v[108:109], v[48:49], v[2:3] op_sel_hi:[1,0,1]
	v_pk_fma_f32 v[4:5], v[110:111], v[48:49], v[4:5] op_sel_hi:[1,0,1]
	s_waitcnt vmcnt(0)
	v_pk_fma_f32 v[6:7], v[112:113], v[124:125], v[6:7] op_sel_hi:[1,0,1]
	v_pk_fma_f32 v[8:9], v[114:115], v[124:125], v[8:9] op_sel_hi:[1,0,1]
	v_pk_fma_f32 v[18:19], v[112:113], v[126:127], v[18:19] op_sel_hi:[1,0,1]
	v_pk_fma_f32 v[20:21], v[114:115], v[126:127], v[20:21] op_sel_hi:[1,0,1]
	v_pk_fma_f32 v[14:15], v[112:113], v[128:129], v[14:15] op_sel_hi:[1,0,1]
	v_pk_fma_f32 v[16:17], v[114:115], v[128:129], v[16:17] op_sel_hi:[1,0,1]
	v_pk_fma_f32 v[10:11], v[112:113], v[130:131], v[10:11] op_sel_hi:[1,0,1]
	v_pk_fma_f32 v[12:13], v[114:115], v[130:131], v[12:13] op_sel_hi:[1,0,1]
	v_pk_fma_f32 v[2:3], v[112:113], v[132:133], v[2:3] op_sel_hi:[1,0,1]
	v_pk_fma_f32 v[4:5], v[114:115], v[132:133], v[4:5] op_sel_hi:[1,0,1]
	ds_write_b128 v75, v[6:9] offset:40960
	ds_write_b128 v75, v[18:21] offset:41344
	ds_write_b128 v75, v[14:17] offset:41728
	ds_write_b128 v75, v[10:13] offset:42112
	ds_write_b128 v75, v[2:5] offset:42496
